# DFT stage 2 unit-to-wave remap: each workgroup takes 4 long-sequence and 4 short-sequence units (balanced per CU/XCD) instead of all-long or all-short workgroups
# baseline (speedup 1.0000x reference)
.LBB0_669:
	s_andn2_b64 vcc, exec, s[0:1]
	s_cbranch_vccnz .LBB0_784
	s_and_b32 s0, s40, 7
	s_lshr_b32 s1, s40, 3
	s_cmp_lt_u32 s0, 4
	s_cbranch_scc0 .Lmy_rm_hi
	s_lshl_b32 s101, s1, 2
	s_add_i32 s101, s101, s0
	s_branch .Lmy_rm_done
.Lmy_rm_hi:
	s_cmp_lt_u32 s1, 32
	s_cbranch_scc0 .Lmy_rm_big
	s_cmp_eq_u32 s0, 4
	s_cbranch_scc0 .Lmy_rm_small
	s_add_i32 s101, s1, 0x400
	s_branch .Lmy_rm_done
.Lmy_rm_small:
	s_mul_i32 s101, s1, 3
	s_add_i32 s101, s101, s0
	s_add_i32 s101, s101, 0x79b
	s_branch .Lmy_rm_done
.Lmy_rm_big:
	s_sub_i32 s0, s0, 4
	s_mul_i32 s0, s0, 0xe0
	s_add_i32 s101, s0, s1
	s_add_i32 s101, s101, 0x400
.Lmy_rm_done:
	s_cmpk_gt_i32 s101, 0x41f
	s_mulk_i32 s41, 0x2200
	s_cbranch_scc0 .LBB0_675
	s_add_i32 s0, s101, 0xfffffbe0
	s_lshr_b32 s1, s0, 3
	s_mul_hi_u32 s0, s0, 0x3e0f83e1
	s_mul_hi_u32 s4, s1, 0x1f07c1f1
	s_lshl_b32 s0, s0, 6
	s_lshr_b32 s4, s4, 2
	s_and_b32 s0, s0, 0xfffff000
	s_mul_i32 s4, s4, 33
	s_addk_i32 s0, 0x4000
	s_and_b32 s15, s101, 7
	s_sub_i32 s14, s1, s4
	s_ashr_i32 s1, s0, 31
	s_lshl_b64 s[10:11], s[0:1], 11
	s_lshl_b32 s4, s14, 17
	s_lshl_b32 s1, s15, 6
	v_readlane_b32 s5, v254, 17
	s_add_u32 s5, s5, s10
	v_readlane_b32 s6, v254, 18
	v_mov_b32_e32 v212, v210
	s_addc_u32 s10, s6, s11
	s_add_u32 s4, s5, s4
	v_ashrrev_i32_e32 v211, 4, v212
	s_addc_u32 s5, s10, 0
	s_lshl_b32 s10, s15, 7
	v_lshlrev_b32_e32 v150, 3, v211
	v_and_b32_e32 v149, 15, v212
	s_add_u32 s10, s4, s10
	s_waitcnt vmcnt(1)
	v_or_b32_e32 v4, 1, v150
	s_addc_u32 s11, s5, 0
	v_lshlrev_b32_e32 v98, 3, v149
	v_ashrrev_i32_e32 v151, 31, v150
	v_ashrrev_i32_e32 v5, 31, v4
	s_waitcnt vmcnt(0)
	v_or_b32_e32 v6, 2, v150
	v_or_b32_e32 v8, 3, v150
	v_lshl_add_u64 v[152:153], s[10:11], 0, v[98:99]
	v_lshlrev_b64 v[2:3], 10, v[150:151]
	v_lshlrev_b64 v[4:5], 10, v[4:5]
	v_ashrrev_i32_e32 v7, 31, v6
	v_ashrrev_i32_e32 v9, 31, v8
	v_lshl_add_u64 v[2:3], v[152:153], 0, v[2:3]
	v_lshl_add_u64 v[4:5], v[152:153], 0, v[4:5]
	v_lshlrev_b64 v[6:7], 10, v[6:7]
	v_lshlrev_b64 v[8:9], 10, v[8:9]
	v_lshl_add_u64 v[6:7], v[152:153], 0, v[6:7]
	v_lshl_add_u64 v[8:9], v[152:153], 0, v[8:9]
	global_load_dwordx2 v[154:155], v[2:3], off
	global_load_dwordx2 v[156:157], v[4:5], off
	global_load_dwordx2 v[158:159], v[6:7], off
	global_load_dwordx2 v[160:161], v[8:9], off
	v_or_b32_e32 v4, 4, v150
	v_ashrrev_i32_e32 v5, 31, v4
	v_or_b32_e32 v6, 5, v150
	v_or_b32_e32 v8, 6, v150
	v_or_b32_e32 v10, 7, v150
	v_lshlrev_b64 v[4:5], 10, v[4:5]
	v_ashrrev_i32_e32 v7, 31, v6
	v_ashrrev_i32_e32 v9, 31, v8
	v_ashrrev_i32_e32 v11, 31, v10
	v_lshl_add_u64 v[4:5], v[152:153], 0, v[4:5]
	v_lshlrev_b64 v[6:7], 10, v[6:7]
	v_lshlrev_b64 v[8:9], 10, v[8:9]
	v_lshlrev_b64 v[10:11], 10, v[10:11]
	v_lshl_add_u64 v[6:7], v[152:153], 0, v[6:7]
	v_lshl_add_u64 v[8:9], v[152:153], 0, v[8:9]
	v_lshl_add_u64 v[10:11], v[152:153], 0, v[10:11]
	global_load_dwordx2 v[164:165], v[4:5], off
	global_load_dwordx2 v[166:167], v[6:7], off
	global_load_dwordx2 v[168:169], v[8:9], off
	global_load_dwordx2 v[172:173], v[10:11], off
	v_lshl_add_u64 v[162:163], v[2:3], 0, s[78:79]
	v_add_u32_e32 v2, 0x41, v150
	v_ashrrev_i32_e32 v3, 31, v2
	v_lshlrev_b64 v[2:3], 10, v[2:3]
	v_lshl_add_u64 v[170:171], v[152:153], 0, v[2:3]
	v_add_u32_e32 v2, 0x42, v150
	v_ashrrev_i32_e32 v3, 31, v2
	v_lshlrev_b64 v[2:3], 10, v[2:3]
	v_lshl_add_u64 v[174:175], v[152:153], 0, v[2:3]
	v_add_u32_e32 v2, 0x43, v150
	v_ashrrev_i32_e32 v3, 31, v2
	v_lshlrev_b64 v[2:3], 10, v[2:3]
	v_lshl_add_u64 v[176:177], v[152:153], 0, v[2:3]
	v_add_u32_e32 v2, 0x44, v150
	v_ashrrev_i32_e32 v3, 31, v2
	v_lshlrev_b64 v[2:3], 10, v[2:3]
	v_lshl_add_u64 v[178:179], v[152:153], 0, v[2:3]
	v_add_u32_e32 v2, 0x45, v150
	v_ashrrev_i32_e32 v3, 31, v2
	v_lshlrev_b64 v[2:3], 10, v[2:3]
	v_lshl_add_u64 v[180:181], v[152:153], 0, v[2:3]
	v_add_u32_e32 v2, 0x46, v150
	v_ashrrev_i32_e32 v3, 31, v2
	v_lshlrev_b64 v[2:3], 10, v[2:3]
	v_lshl_add_u64 v[182:183], v[152:153], 0, v[2:3]
	v_add_u32_e32 v2, 0x47, v150
	v_ashrrev_i32_e32 v3, 31, v2
	v_lshlrev_b64 v[2:3], 10, v[2:3]
	s_movk_i32 s4, 0x220
	v_mov_b32_e32 v46, 0
	v_lshlrev_b32_e32 v148, 2, v149
	v_add_u32_e32 v98, 32, v150
	v_lshl_add_u64 v[184:185], v[152:153], 0, v[2:3]
	v_mad_u32_u24 v213, v149, s4, 0
	s_mov_b32 s20, 0
	s_mov_b64 s[10:11], -1
	v_mov_b32_e32 v47, v46
	v_mov_b32_e32 v48, v46
	v_mov_b32_e32 v49, v46
	v_mov_b32_e32 v54, v46
	v_mov_b32_e32 v55, v46
	v_mov_b32_e32 v56, v46
	v_mov_b32_e32 v57, v46
	v_mov_b32_e32 v58, v46
	v_mov_b32_e32 v59, v46
	v_mov_b32_e32 v60, v46
	v_mov_b32_e32 v61, v46
	v_mov_b32_e32 v62, v46
	v_mov_b32_e32 v63, v46
	v_mov_b32_e32 v64, v46
	v_mov_b32_e32 v65, v46
	v_mov_b32_e32 v34, v46
	v_mov_b32_e32 v35, v46
	v_mov_b32_e32 v36, v46
	v_mov_b32_e32 v37, v46
	v_mov_b32_e32 v38, v46
	v_mov_b32_e32 v39, v46
	v_mov_b32_e32 v40, v46
	v_mov_b32_e32 v41, v46
	v_mov_b32_e32 v42, v46
	v_mov_b32_e32 v43, v46
	v_mov_b32_e32 v44, v46
	v_mov_b32_e32 v45, v46
	v_mov_b32_e32 v50, v46
	v_mov_b32_e32 v51, v46
	v_mov_b32_e32 v52, v46
	v_mov_b32_e32 v53, v46
	v_mov_b32_e32 v82, v46
	v_mov_b32_e32 v83, v46
	v_mov_b32_e32 v84, v46
	v_mov_b32_e32 v85, v46
	v_mov_b32_e32 v86, v46
	v_mov_b32_e32 v87, v46
	v_mov_b32_e32 v88, v46
	v_mov_b32_e32 v89, v46
	v_mov_b32_e32 v90, v46
	v_mov_b32_e32 v91, v46
	v_mov_b32_e32 v92, v46
	v_mov_b32_e32 v93, v46
	v_mov_b32_e32 v94, v46
	v_mov_b32_e32 v95, v46
	v_mov_b32_e32 v96, v46
	v_mov_b32_e32 v97, v46
	v_mov_b32_e32 v66, v46
	v_mov_b32_e32 v67, v46
	v_mov_b32_e32 v68, v46
	v_mov_b32_e32 v69, v46
	v_mov_b32_e32 v70, v46
	v_mov_b32_e32 v71, v46
	v_mov_b32_e32 v72, v46
	v_mov_b32_e32 v73, v46
	v_mov_b32_e32 v74, v46
	v_mov_b32_e32 v75, v46
	v_mov_b32_e32 v76, v46
	v_mov_b32_e32 v77, v46
	v_mov_b32_e32 v78, v46
	v_mov_b32_e32 v79, v46
	v_mov_b32_e32 v80, v46
	v_mov_b32_e32 v81, v46
	v_mov_b32_e32 v18, v46
	v_mov_b32_e32 v19, v46
	v_mov_b32_e32 v20, v46
	v_mov_b32_e32 v21, v46
	v_mov_b32_e32 v22, v46
	v_mov_b32_e32 v23, v46
	v_mov_b32_e32 v24, v46
	v_mov_b32_e32 v25, v46
	v_mov_b32_e32 v26, v46
	v_mov_b32_e32 v27, v46
	v_mov_b32_e32 v28, v46
	v_mov_b32_e32 v29, v46
	v_mov_b32_e32 v30, v46
	v_mov_b32_e32 v31, v46
	v_mov_b32_e32 v32, v46
	v_mov_b32_e32 v33, v46
	v_mov_b32_e32 v14, v46
	v_mov_b32_e32 v15, v46
	v_mov_b32_e32 v16, v46
	v_mov_b32_e32 v17, v46
	v_mov_b32_e32 v10, v46
	v_mov_b32_e32 v11, v46
	v_mov_b32_e32 v12, v46
	v_mov_b32_e32 v13, v46
	v_mov_b32_e32 v6, v46
	v_mov_b32_e32 v7, v46
	v_mov_b32_e32 v8, v46
	v_mov_b32_e32 v9, v46
	v_mov_b32_e32 v2, v46
	v_mov_b32_e32 v3, v46
	v_mov_b32_e32 v4, v46
	v_mov_b32_e32 v5, v46
	v_mov_b32_e32 v100, v46
	v_mov_b32_e32 v101, v46
	v_mov_b32_e32 v102, v46
	v_mov_b32_e32 v103, v46
	v_mov_b32_e32 v104, v46
	v_mov_b32_e32 v105, v46
	v_mov_b32_e32 v106, v46
	v_mov_b32_e32 v107, v46
	v_mov_b32_e32 v108, v46
	v_mov_b32_e32 v109, v46
	v_mov_b32_e32 v110, v46
	v_mov_b32_e32 v111, v46
	v_mov_b32_e32 v112, v46
	v_mov_b32_e32 v113, v46
	v_mov_b32_e32 v114, v46
	v_mov_b32_e32 v115, v46
	v_mov_b32_e32 v116, v46
	v_mov_b32_e32 v117, v46
	v_mov_b32_e32 v118, v46
	v_mov_b32_e32 v119, v46
	v_mov_b32_e32 v120, v46
	v_mov_b32_e32 v121, v46
	v_mov_b32_e32 v122, v46
	v_mov_b32_e32 v123, v46
	v_mov_b32_e32 v124, v46
	v_mov_b32_e32 v125, v46
	v_mov_b32_e32 v126, v46
	v_mov_b32_e32 v127, v46
	v_mov_b32_e32 v128, v46
	v_mov_b32_e32 v129, v46
	v_mov_b32_e32 v130, v46
	v_mov_b32_e32 v131, v46
	s_branch .LBB0_673

.LBB0_708:
	s_mov_b64 s[10:11], 0
	s_cmpk_gt_i32 s101, 0x45f
	s_mov_b64 s[14:15], 0
	s_cbranch_scc1 .LBB0_745
	s_sub_i32 s0, s101, 64
	s_lshr_b32 s0, s0, 3
	s_mul_hi_u32 s1, s0, 0x1f07c1f1
	s_lshr_b32 s1, s1, 2
	s_mul_i32 s1, s1, 33
	s_sub_i32 s30, s0, s1
	v_mov_b32_e32 v212, v210
	s_lshl_b32 s0, s30, 17
	v_readlane_b32 s1, v254, 25
	s_add_u32 s0, s1, s0
	v_ashrrev_i32_e32 v211, 4, v212
	v_readlane_b32 s1, v254, 26
	s_addc_u32 s1, s1, 0
	v_lshlrev_b32_e32 v150, 3, v211
	v_and_b32_e32 v149, 15, v212
	s_add_u32 s0, s0, s21
	v_or_b32_e32 v4, 1, v150
	s_addc_u32 s1, s1, 0
	v_lshlrev_b32_e32 v98, 3, v149
	v_ashrrev_i32_e32 v151, 31, v150
	v_ashrrev_i32_e32 v5, 31, v4
	v_or_b32_e32 v6, 2, v150
	v_or_b32_e32 v8, 3, v150
	v_lshl_add_u64 v[152:153], s[0:1], 0, v[98:99]
	v_lshlrev_b64 v[2:3], 10, v[150:151]
	v_lshlrev_b64 v[4:5], 10, v[4:5]
	v_ashrrev_i32_e32 v7, 31, v6
	v_ashrrev_i32_e32 v9, 31, v8
	v_lshl_add_u64 v[2:3], v[152:153], 0, v[2:3]
	v_lshl_add_u64 v[4:5], v[152:153], 0, v[4:5]
	v_lshlrev_b64 v[6:7], 10, v[6:7]
	v_lshlrev_b64 v[8:9], 10, v[8:9]
	v_lshl_add_u64 v[6:7], v[152:153], 0, v[6:7]
	v_lshl_add_u64 v[8:9], v[152:153], 0, v[8:9]
	global_load_dwordx2 v[154:155], v[2:3], off
	global_load_dwordx2 v[156:157], v[4:5], off
	global_load_dwordx2 v[158:159], v[6:7], off
	global_load_dwordx2 v[160:161], v[8:9], off
	v_or_b32_e32 v4, 4, v150
	v_ashrrev_i32_e32 v5, 31, v4
	v_or_b32_e32 v6, 5, v150
	v_or_b32_e32 v8, 6, v150
	v_or_b32_e32 v10, 7, v150
	v_lshlrev_b64 v[4:5], 10, v[4:5]
	v_ashrrev_i32_e32 v7, 31, v6
	v_ashrrev_i32_e32 v9, 31, v8
	v_ashrrev_i32_e32 v11, 31, v10
	v_lshl_add_u64 v[4:5], v[152:153], 0, v[4:5]
	v_lshlrev_b64 v[6:7], 10, v[6:7]
	v_lshlrev_b64 v[8:9], 10, v[8:9]
	v_lshlrev_b64 v[10:11], 10, v[10:11]
	v_lshl_add_u64 v[6:7], v[152:153], 0, v[6:7]
	v_lshl_add_u64 v[8:9], v[152:153], 0, v[8:9]
	v_lshl_add_u64 v[10:11], v[152:153], 0, v[10:11]
	global_load_dwordx2 v[164:165], v[4:5], off
	global_load_dwordx2 v[166:167], v[6:7], off
	global_load_dwordx2 v[168:169], v[8:9], off
	global_load_dwordx2 v[172:173], v[10:11], off
	v_lshl_add_u64 v[162:163], v[2:3], 0, s[78:79]
	v_add_u32_e32 v2, 0x41, v150
	v_ashrrev_i32_e32 v3, 31, v2
	v_lshlrev_b64 v[2:3], 10, v[2:3]
	v_lshl_add_u64 v[170:171], v[152:153], 0, v[2:3]
	v_add_u32_e32 v2, 0x42, v150
	v_ashrrev_i32_e32 v3, 31, v2
	v_lshlrev_b64 v[2:3], 10, v[2:3]
	v_lshl_add_u64 v[174:175], v[152:153], 0, v[2:3]
	v_add_u32_e32 v2, 0x43, v150
	v_ashrrev_i32_e32 v3, 31, v2
	v_lshlrev_b64 v[2:3], 10, v[2:3]
	v_lshl_add_u64 v[176:177], v[152:153], 0, v[2:3]
	v_add_u32_e32 v2, 0x44, v150
	v_ashrrev_i32_e32 v3, 31, v2
	v_lshlrev_b64 v[2:3], 10, v[2:3]
	v_lshl_add_u64 v[178:179], v[152:153], 0, v[2:3]
	v_add_u32_e32 v2, 0x45, v150
	v_ashrrev_i32_e32 v3, 31, v2
	v_lshlrev_b64 v[2:3], 10, v[2:3]
	v_lshl_add_u64 v[180:181], v[152:153], 0, v[2:3]
	v_add_u32_e32 v2, 0x46, v150
	v_ashrrev_i32_e32 v3, 31, v2
	v_lshlrev_b64 v[2:3], 10, v[2:3]
	v_lshl_add_u64 v[182:183], v[152:153], 0, v[2:3]
	v_add_u32_e32 v2, 0x47, v150
	v_ashrrev_i32_e32 v3, 31, v2
	v_lshlrev_b64 v[2:3], 10, v[2:3]
	s_movk_i32 s0, 0x220
	v_mov_b32_e32 v46, 0
	v_lshlrev_b32_e32 v148, 2, v149
	v_add_u32_e32 v98, 32, v150
	v_lshl_add_u64 v[184:185], v[152:153], 0, v[2:3]
	v_mad_u32_u24 v213, v149, s0, 0
	s_mov_b32 s31, 0
	s_mov_b64 s[0:1], -1
	v_mov_b32_e32 v47, v46
	v_mov_b32_e32 v48, v46
	v_mov_b32_e32 v49, v46
	v_mov_b32_e32 v54, v46
	v_mov_b32_e32 v55, v46
	v_mov_b32_e32 v56, v46
	v_mov_b32_e32 v57, v46
	v_mov_b32_e32 v58, v46
	v_mov_b32_e32 v59, v46
	v_mov_b32_e32 v60, v46
	v_mov_b32_e32 v61, v46
	v_mov_b32_e32 v62, v46
	v_mov_b32_e32 v63, v46
	v_mov_b32_e32 v64, v46
	v_mov_b32_e32 v65, v46
	v_mov_b32_e32 v34, v46
	v_mov_b32_e32 v35, v46
	v_mov_b32_e32 v36, v46
	v_mov_b32_e32 v37, v46
	v_mov_b32_e32 v38, v46
	v_mov_b32_e32 v39, v46
	v_mov_b32_e32 v40, v46
	v_mov_b32_e32 v41, v46
	v_mov_b32_e32 v42, v46
	v_mov_b32_e32 v43, v46
	v_mov_b32_e32 v44, v46
	v_mov_b32_e32 v45, v46
	v_mov_b32_e32 v50, v46
	v_mov_b32_e32 v51, v46
	v_mov_b32_e32 v52, v46
	v_mov_b32_e32 v53, v46
	v_mov_b32_e32 v82, v46
	v_mov_b32_e32 v83, v46
	v_mov_b32_e32 v84, v46
	v_mov_b32_e32 v85, v46
	v_mov_b32_e32 v86, v46
	v_mov_b32_e32 v87, v46
	v_mov_b32_e32 v88, v46
	v_mov_b32_e32 v89, v46
	v_mov_b32_e32 v90, v46
	v_mov_b32_e32 v91, v46
	v_mov_b32_e32 v92, v46
	v_mov_b32_e32 v93, v46
	v_mov_b32_e32 v94, v46
	v_mov_b32_e32 v95, v46
	v_mov_b32_e32 v96, v46
	v_mov_b32_e32 v97, v46
	v_mov_b32_e32 v66, v46
	v_mov_b32_e32 v67, v46
	v_mov_b32_e32 v68, v46
	v_mov_b32_e32 v69, v46
	v_mov_b32_e32 v70, v46
	v_mov_b32_e32 v71, v46
	v_mov_b32_e32 v72, v46
	v_mov_b32_e32 v73, v46
	v_mov_b32_e32 v74, v46
	v_mov_b32_e32 v75, v46
	v_mov_b32_e32 v76, v46
	v_mov_b32_e32 v77, v46
	v_mov_b32_e32 v78, v46
	v_mov_b32_e32 v79, v46
	v_mov_b32_e32 v80, v46
	v_mov_b32_e32 v81, v46
	v_mov_b32_e32 v18, v46
	v_mov_b32_e32 v19, v46
	v_mov_b32_e32 v20, v46
	v_mov_b32_e32 v21, v46
	v_mov_b32_e32 v22, v46
	v_mov_b32_e32 v23, v46
	v_mov_b32_e32 v24, v46
	v_mov_b32_e32 v25, v46
	v_mov_b32_e32 v26, v46
	v_mov_b32_e32 v27, v46
	v_mov_b32_e32 v28, v46
	v_mov_b32_e32 v29, v46
	v_mov_b32_e32 v30, v46
	v_mov_b32_e32 v31, v46
	v_mov_b32_e32 v32, v46
	v_mov_b32_e32 v33, v46
	v_mov_b32_e32 v14, v46
	v_mov_b32_e32 v15, v46
	v_mov_b32_e32 v16, v46
	v_mov_b32_e32 v17, v46
	v_mov_b32_e32 v10, v46
	v_mov_b32_e32 v11, v46
	v_mov_b32_e32 v12, v46
	v_mov_b32_e32 v13, v46
	v_mov_b32_e32 v6, v46
	v_mov_b32_e32 v7, v46
	v_mov_b32_e32 v8, v46
	v_mov_b32_e32 v9, v46
	v_mov_b32_e32 v2, v46
	v_mov_b32_e32 v3, v46
	v_mov_b32_e32 v4, v46
	v_mov_b32_e32 v5, v46
	v_mov_b32_e32 v100, v46
	v_mov_b32_e32 v101, v46
	v_mov_b32_e32 v102, v46
	v_mov_b32_e32 v103, v46
	v_mov_b32_e32 v104, v46
	v_mov_b32_e32 v105, v46
	v_mov_b32_e32 v106, v46
	v_mov_b32_e32 v107, v46
	v_mov_b32_e32 v108, v46
	v_mov_b32_e32 v109, v46
	v_mov_b32_e32 v110, v46
	v_mov_b32_e32 v111, v46
	v_mov_b32_e32 v112, v46
	v_mov_b32_e32 v113, v46
	v_mov_b32_e32 v114, v46
	v_mov_b32_e32 v115, v46
	v_mov_b32_e32 v116, v46
	v_mov_b32_e32 v117, v46
	v_mov_b32_e32 v118, v46
	v_mov_b32_e32 v119, v46
	v_mov_b32_e32 v120, v46
	v_mov_b32_e32 v121, v46
	v_mov_b32_e32 v122, v46
	v_mov_b32_e32 v123, v46
	v_mov_b32_e32 v124, v46
	v_mov_b32_e32 v125, v46
	v_mov_b32_e32 v126, v46
	v_mov_b32_e32 v127, v46
	v_mov_b32_e32 v128, v46
	v_mov_b32_e32 v129, v46
	v_mov_b32_e32 v130, v46
	v_mov_b32_e32 v131, v46
	s_branch .LBB0_711

.LBB0_745:
	s_and_b64 vcc, exec, s[10:11]
	s_cbranch_vccz .LBB0_782
	s_ashr_i32 s0, s101, 4
	s_mul_hi_i32 s1, s0, 0x3e0f83e1
	s_lshr_b32 s4, s1, 31
	s_ashr_i32 s1, s1, 3
	s_add_i32 s1, s1, s4
	s_mul_i32 s4, s1, 33
	s_sub_i32 s0, s0, s4
	s_lshl_b32 s10, s1, 13
	s_and_b32 s18, s101, 7
	s_ashr_i32 s11, s10, 31
	s_ashr_i32 s1, s0, 31
	s_lshl_b64 s[12:13], s[10:11], 11
	s_lshl_b64 s[20:21], s[0:1], 18
	s_lshl_b32 s11, s18, 6
	v_readlane_b32 s1, v254, 17
	s_add_u32 s1, s1, s12
	v_readlane_b32 s4, v254, 18
	s_addc_u32 s4, s4, s13
	s_add_u32 s1, s1, s20
	s_addc_u32 s4, s4, s21
	v_ashrrev_i32_e32 v186, 4, v210
	s_lshl_b32 s5, s18, 7
	v_and_b32_e32 v149, 15, v210
	s_add_u32 s30, s1, s5
	v_lshlrev_b32_e32 v150, 3, v186
	s_addc_u32 s31, s4, 0
	v_lshlrev_b32_e32 v98, 3, v149
	v_ashrrev_i32_e32 v151, 31, v150
	s_waitcnt vmcnt(0)
	v_or_b32_e32 v8, 1, v150
	v_or_b32_e32 v10, 2, v150
	v_or_b32_e32 v12, 3, v150
	v_lshl_add_u64 v[2:3], s[30:31], 0, v[98:99]
	v_lshlrev_b64 v[4:5], 10, v[150:151]
	v_ashrrev_i32_e32 v9, 31, v8
	v_ashrrev_i32_e32 v11, 31, v10
	v_ashrrev_i32_e32 v13, 31, v12
	v_lshl_add_u64 v[6:7], v[2:3], 0, v[4:5]
	v_lshlrev_b64 v[8:9], 10, v[8:9]
	v_lshlrev_b64 v[10:11], 10, v[10:11]
	v_lshlrev_b64 v[12:13], 10, v[12:13]
	v_lshl_add_u64 v[8:9], v[2:3], 0, v[8:9]
	v_lshl_add_u64 v[10:11], v[2:3], 0, v[10:11]
	v_lshl_add_u64 v[12:13], v[2:3], 0, v[12:13]
	global_load_dwordx2 v[152:153], v[6:7], off
	global_load_dwordx2 v[154:155], v[8:9], off
	global_load_dwordx2 v[156:157], v[10:11], off
	global_load_dwordx2 v[158:159], v[12:13], off
	v_or_b32_e32 v6, 4, v150
	v_ashrrev_i32_e32 v7, 31, v6
	v_or_b32_e32 v8, 5, v150
	v_or_b32_e32 v10, 6, v150
	v_or_b32_e32 v12, 7, v150
	v_lshlrev_b64 v[6:7], 10, v[6:7]
	v_ashrrev_i32_e32 v9, 31, v8
	v_ashrrev_i32_e32 v11, 31, v10
	v_ashrrev_i32_e32 v13, 31, v12
	v_lshl_add_u64 v[6:7], v[2:3], 0, v[6:7]
	v_lshlrev_b64 v[8:9], 10, v[8:9]
	v_lshlrev_b64 v[10:11], 10, v[10:11]
	v_lshlrev_b64 v[12:13], 10, v[12:13]
	v_lshl_add_u64 v[8:9], v[2:3], 0, v[8:9]
	v_lshl_add_u64 v[10:11], v[2:3], 0, v[10:11]
	v_lshl_add_u64 v[2:3], v[2:3], 0, v[12:13]
	global_load_dwordx2 v[160:161], v[6:7], off
	global_load_dwordx2 v[162:163], v[8:9], off
	global_load_dwordx2 v[164:165], v[10:11], off
	global_load_dwordx2 v[166:167], v[2:3], off
	s_lshl_b32 s1, s101, 3
	s_and_b32 s1, s1, 64
	s_add_u32 s12, s20, s12
	v_or_b32_e32 v2, s1, v149
	s_movk_i32 s4, 0x110
	s_addc_u32 s13, s21, s13
	v_mad_u32_u24 v187, v2, s4, 0
	v_lshl_add_u64 v[2:3], s[12:13], 0, v[4:5]
	v_or3_b32 v2, v2, s5, v98
	v_readlane_b32 s4, v255, 17
	v_readlane_b32 s5, v255, 18
	v_mov_b32_e32 v34, 0
	v_lshlrev_b32_e32 v148, 2, v149
	v_lshl_add_u64 v[168:169], s[4:5], 0, v[2:3]
	s_mov_b32 s20, 0
	v_mov_b32_e32 v98, v150
	v_mov_b32_e32 v35, v34
	v_mov_b32_e32 v36, v34
	v_mov_b32_e32 v37, v34
	v_mov_b32_e32 v38, v34
	v_mov_b32_e32 v39, v34
	v_mov_b32_e32 v40, v34
	v_mov_b32_e32 v41, v34
	v_mov_b32_e32 v42, v34
	v_mov_b32_e32 v43, v34
	v_mov_b32_e32 v44, v34
	v_mov_b32_e32 v45, v34
	v_mov_b32_e32 v46, v34
	v_mov_b32_e32 v47, v34
	v_mov_b32_e32 v48, v34
	v_mov_b32_e32 v49, v34
	v_mov_b32_e32 v18, v34
	v_mov_b32_e32 v19, v34
	v_mov_b32_e32 v20, v34
	v_mov_b32_e32 v21, v34
	v_mov_b32_e32 v22, v34
	v_mov_b32_e32 v23, v34
	v_mov_b32_e32 v24, v34
	v_mov_b32_e32 v25, v34
	v_mov_b32_e32 v26, v34
	v_mov_b32_e32 v27, v34
	v_mov_b32_e32 v28, v34
	v_mov_b32_e32 v29, v34
	v_mov_b32_e32 v30, v34
	v_mov_b32_e32 v31, v34
	v_mov_b32_e32 v32, v34
	v_mov_b32_e32 v33, v34
	v_mov_b32_e32 v82, v34
	v_mov_b32_e32 v83, v34
	v_mov_b32_e32 v84, v34
	v_mov_b32_e32 v85, v34
	v_mov_b32_e32 v86, v34
	v_mov_b32_e32 v87, v34
	v_mov_b32_e32 v88, v34
	v_mov_b32_e32 v89, v34
	v_mov_b32_e32 v90, v34
	v_mov_b32_e32 v91, v34
	v_mov_b32_e32 v92, v34
	v_mov_b32_e32 v93, v34
	v_mov_b32_e32 v94, v34
	v_mov_b32_e32 v95, v34
	v_mov_b32_e32 v96, v34
	v_mov_b32_e32 v97, v34
	v_mov_b32_e32 v66, v34
	v_mov_b32_e32 v67, v34
	v_mov_b32_e32 v68, v34
	v_mov_b32_e32 v69, v34
	v_mov_b32_e32 v70, v34
	v_mov_b32_e32 v71, v34
	v_mov_b32_e32 v72, v34
	v_mov_b32_e32 v73, v34
	v_mov_b32_e32 v74, v34
	v_mov_b32_e32 v75, v34
	v_mov_b32_e32 v76, v34
	v_mov_b32_e32 v77, v34
	v_mov_b32_e32 v78, v34
	v_mov_b32_e32 v79, v34
	v_mov_b32_e32 v80, v34
	v_mov_b32_e32 v81, v34
	v_mov_b32_e32 v50, v34
	v_mov_b32_e32 v51, v34
	v_mov_b32_e32 v52, v34
	v_mov_b32_e32 v53, v34
	v_mov_b32_e32 v54, v34
	v_mov_b32_e32 v55, v34
	v_mov_b32_e32 v56, v34
	v_mov_b32_e32 v57, v34
	v_mov_b32_e32 v58, v34
	v_mov_b32_e32 v59, v34
	v_mov_b32_e32 v60, v34
	v_mov_b32_e32 v61, v34
	v_mov_b32_e32 v62, v34
	v_mov_b32_e32 v63, v34
	v_mov_b32_e32 v64, v34
	v_mov_b32_e32 v65, v34
	v_mov_b32_e32 v14, v34
	v_mov_b32_e32 v15, v34
	v_mov_b32_e32 v16, v34
	v_mov_b32_e32 v17, v34
	v_mov_b32_e32 v2, v34
	v_mov_b32_e32 v3, v34
	v_mov_b32_e32 v4, v34
	v_mov_b32_e32 v5, v34
	v_mov_b32_e32 v6, v34
	v_mov_b32_e32 v7, v34
	v_mov_b32_e32 v8, v34
	v_mov_b32_e32 v9, v34
	v_mov_b32_e32 v10, v34
	v_mov_b32_e32 v11, v34
	v_mov_b32_e32 v12, v34
	v_mov_b32_e32 v13, v34
	v_mov_b32_e32 v100, v34
	v_mov_b32_e32 v101, v34
	v_mov_b32_e32 v102, v34
	v_mov_b32_e32 v103, v34
	v_mov_b32_e32 v104, v34
	v_mov_b32_e32 v105, v34
	v_mov_b32_e32 v106, v34
	v_mov_b32_e32 v107, v34
	v_mov_b32_e32 v108, v34
	v_mov_b32_e32 v109, v34
	v_mov_b32_e32 v110, v34
	v_mov_b32_e32 v111, v34
	v_mov_b32_e32 v112, v34
	v_mov_b32_e32 v113, v34
	v_mov_b32_e32 v114, v34
	v_mov_b32_e32 v115, v34
	v_mov_b32_e32 v116, v34
	v_mov_b32_e32 v117, v34
	v_mov_b32_e32 v118, v34
	v_mov_b32_e32 v119, v34
	v_mov_b32_e32 v120, v34
	v_mov_b32_e32 v121, v34
	v_mov_b32_e32 v122, v34
	v_mov_b32_e32 v123, v34
	v_mov_b32_e32 v124, v34
	v_mov_b32_e32 v125, v34
	v_mov_b32_e32 v126, v34
	v_mov_b32_e32 v127, v34
	v_mov_b32_e32 v128, v34
	v_mov_b32_e32 v129, v34
	v_mov_b32_e32 v130, v34
	v_mov_b32_e32 v131, v34
	s_branch .LBB0_748
